# GEMM1 late-start delay for workgroups 128..255 set to 440 x64 clocks
# baseline (speedup 1.0000x reference)
.LBB0_106:
	v_writelane_b32 v246, s52, 32
	s_nop 1
	v_writelane_b32 v246, s53, 33
	v_writelane_b32 v246, s54, 34
	v_writelane_b32 v246, s55, 35
	v_writelane_b32 v246, s56, 36
	v_writelane_b32 v246, s57, 37
	v_writelane_b32 v246, s58, 38
	v_writelane_b32 v246, s59, 39
	v_writelane_b32 v246, s60, 40
	v_writelane_b32 v246, s61, 41
	v_writelane_b32 v246, s62, 42
	v_writelane_b32 v246, s63, 43
	v_writelane_b32 v246, s64, 44
	v_writelane_b32 v246, s65, 45
	v_writelane_b32 v246, s66, 46
	v_writelane_b32 v246, s67, 47
	s_or_b64 exec, exec, s[18:19]
	s_bitcmp0_b32 s2, 7
	s_cbranch_scc1 .Lg1d_skip
	s_sleep 127
	s_sleep 127
	s_sleep 127
	s_sleep 59
